# phases 6 and 3 GEMM main loops: LDS-DMA A in full lines, B staged one k-tile ahead behind MFMAs, progressive fragment refill
# speedup vs baseline: 1.0452x; 1.0153x over previous
.LBB0_1102:
	s_or_b64 exec, exec, s[4:5]
	s_mov_b32 s14, 48
	v_readlane_b32 s0, v245, 13
	s_barrier
	s_cmp_ge_i32 s0, s14
	s_mul_i32 s68, s85, 5
	s_cbranch_scc1 .LBB0_1113
	s_lshl_b32 s0, s85, 20
	s_lshl_b64 s[4:5], s[0:1], 2
	v_readlane_b32 s44, v247, 25
	v_readlane_b32 s45, v247, 26
	v_mov_b32_e32 v6, v187
	s_add_u32 s15, s44, s4
	s_addc_u32 s34, s45, s5
	v_readlane_b32 s4, v245, 14
	v_readlane_b32 s5, v245, 15
	s_lshl_b64 s[4:5], s[4:5], 2
	s_add_u32 s4, s15, s4
	s_addc_u32 s5, s34, s5
	v_readlane_b32 s6, v246, 63
	v_readlane_b32 s7, v245, 0
	v_readlane_b32 s35, v245, 16
	v_readlane_b32 s37, v245, 13
	v_and_b32_e32 v7, 31, v6
	v_ashrrev_i32_e32 v9, 5, v6
	v_lshlrev_b32_e32 v198, 2, v7
	v_bfe_u32 v199, v6, 5, 1
	v_and_b32_e32 v207, 0xffffffc0, v6
	v_lshl_or_b32 v200, v9, 12, v198
	v_lshlrev_b32_e32 v177, 2, v200
	v_readfirstlane_b32 s75, v6
	s_and_b32 s75, s75, 0xc0
	s_lshl_b32 s75, s75, 8
	s_movk_i32 s76, 0x2000
	v_lshrrev_b32_e32 v2, 1, v7
	v_and_b32_e32 v2, 7, v2
	v_xor_b32_e32 v2, v2, v199
	v_lshlrev_b32_e32 v2, 4, v2
	v_lshl_or_b32 v2, v7, 7, v2
	v_or_b32_e32 v170, s75, v2
	v_xor_b32_e32 v171, 32, v170
	v_xor_b32_e32 v172, 64, v170
	v_xor_b32_e32 v173, 0x60, v170
	v_lshrrev_b32_e32 v2, 2, v7
	v_and_b32_e32 v2, 3, v2
	v_xor_b32_e32 v3, v2, v199
	v_lshlrev_b32_e32 v3, 4, v3
	v_lshl_or_b32 v3, v7, 6, v3
	v_add_u32_e32 v174, 0x10000, v3
	v_xor_b32_e32 v175, 32, v174
	v_lshrrev_b32_e32 v3, 1, v9
	v_xor_b32_e32 v3, v3, v2
	v_lshlrev_b32_e32 v3, 4, v3
	v_and_b32_e32 v4, 1, v9
	v_lshl_or_b32 v3, v4, 3, v3
	v_lshl_or_b32 v3, v7, 6, v3
	v_add_u32_e32 v176, 0x10000, v3
	v_and_b32_e32 v2, 7, v6
	v_bfe_u32 v3, v6, 4, 2
	v_xor_b32_e32 v2, v2, v3
	v_lshlrev_b32_e32 v204, 4, v2
	v_xor_b32_e32 v205, 64, v204
	s_add_u32 s56, s6, 0xfffff000
	s_addc_u32 s57, s7, -1
	v_lshrrev_b32_e32 v2, 3, v6
	v_and_b32_e32 v2, 7, v2
	v_and_b32_e32 v3, 0xc0, v6
	v_or_b32_e32 v2, v2, v3
	v_lshl_add_u32 v162, v2, 11, v204
	v_lshl_add_u32 v163, v2, 11, v205
	v_lshl_add_u32 v164, v2, 11, v204
	v_lshl_add_u32 v165, v2, 11, v205
	v_lshl_add_u32 v166, v2, 11, v204
	v_lshl_add_u32 v167, v2, 11, v205
	v_lshl_add_u32 v168, v2, 11, v204
	v_lshl_add_u32 v169, v2, 11, v205
	v_add_u32_e32 v162, 0x1000, v162
	v_add_u32_e32 v163, 0x4c00, v163
	v_add_u32_e32 v164, 0x8800, v164
	v_add_u32_e32 v165, 0xc400, v165
	v_add_u32_e32 v166, 0x11000, v166
	v_add_u32_e32 v167, 0x14c00, v167
	v_add_u32_e32 v168, 0x18800, v168
	v_add_u32_e32 v169, 0x1c400, v169
	s_lshl_b32 s0, s35, 1
	s_and_b32 s40, s0, 30
	s_lshl_b32 s40, s40, 6
	s_add_u32 s40, s56, s40
	s_addc_u32 s41, s57, 0
	s_mov_b32 m0, s75
	s_nop 0
	global_load_lds_dwordx4 v162, s[40:41]
	global_load_lds_dwordx4 v163, s[40:41] offset:1024
	global_load_lds_dwordx4 v164, s[40:41] offset:2048
	global_load_lds_dwordx4 v165, s[40:41] offset:3072
	s_add_u32 m0, m0, 0x1000
	s_nop 0
	global_load_lds_dwordx4 v166, s[40:41]
	global_load_lds_dwordx4 v167, s[40:41] offset:1024
	global_load_lds_dwordx4 v168, s[40:41] offset:2048
	global_load_lds_dwordx4 v169, s[40:41] offset:3072
	s_and_b32 s58, s0, 31
	s_lshl_b32 s58, s58, 17
	s_add_u32 s58, s4, s58
	s_addc_u32 s59, s5, 0
	s_add_u32 s60, s58, 0x1000
	s_addc_u32 s61, s59, 0
	s_add_u32 s62, s58, s33
	s_addc_u32 s63, s59, 0
	s_add_u32 s64, s58, 0x3000
	s_addc_u32 s65, s59, 0
	global_load_dwordx4 v[130:133], v177, s[58:59]
	global_load_dwordx4 v[134:137], v177, s[60:61]
	global_load_dwordx4 v[138:141], v177, s[62:63]
	global_load_dwordx4 v[142:145], v177, s[64:65]
	s_add_i32 s0, s0, 1
	s_and_b32 s58, s0, 31
	s_lshl_b32 s58, s58, 17
	s_add_u32 s58, s4, s58
	s_addc_u32 s59, s5, 0
	s_add_u32 s60, s58, 0x1000
	s_addc_u32 s61, s59, 0
	s_add_u32 s62, s58, s33
	s_addc_u32 s63, s59, 0
	s_add_u32 s64, s58, 0x3000
	s_addc_u32 s65, s59, 0
	global_load_dwordx4 v[146:149], v177, s[58:59]
	global_load_dwordx4 v[150:153], v177, s[60:61]
	global_load_dwordx4 v[154:157], v177, s[62:63]
	global_load_dwordx4 v[158:161], v177, s[64:65]
	s_waitcnt vmcnt(4)
	v_cvt_pk_bf16_f32 v190, v130, v134
	v_cvt_pk_bf16_f32 v191, v138, v142
	v_cvt_pk_bf16_f32 v192, v131, v135
	v_cvt_pk_bf16_f32 v193, v139, v143
	ds_write2st64_b64 v176, v[190:191], v[192:193] offset0:0 offset1:4
	v_cvt_pk_bf16_f32 v194, v132, v136
	v_cvt_pk_bf16_f32 v195, v140, v144
	v_cvt_pk_bf16_f32 v190, v133, v137
	v_cvt_pk_bf16_f32 v191, v141, v145
	ds_write2st64_b64 v176, v[194:195], v[190:191] offset0:8 offset1:12
	s_add_i32 s0, s0, 1
	s_and_b32 s58, s0, 31
	s_lshl_b32 s58, s58, 17
	s_add_u32 s58, s4, s58
	s_addc_u32 s59, s5, 0
	s_add_u32 s60, s58, 0x1000
	s_addc_u32 s61, s59, 0
	s_add_u32 s62, s58, s33
	s_addc_u32 s63, s59, 0
	s_add_u32 s64, s58, 0x3000
	s_addc_u32 s65, s59, 0
	global_load_dwordx4 v[130:133], v177, s[58:59]
	global_load_dwordx4 v[134:137], v177, s[60:61]
	global_load_dwordx4 v[138:141], v177, s[62:63]
	global_load_dwordx4 v[142:145], v177, s[64:65]
	ds_read_b128 v[220:223], v170
	ds_read_b128 v[224:227], v170 offset:4096
	s_branch .LBB0_1105

.LBB0_1107:
	v_mov_b32_e32 v2, 0
	s_mov_b32 s39, 0
	s_mov_b32 s74, 2
	v_mov_b32_e32 v3, v2
	v_mov_b32_e32 v4, v2
	v_mov_b32_e32 v5, v2
	v_mov_b32_e32 v6, v2
	v_mov_b32_e32 v7, v2
	v_mov_b32_e32 v8, v2
	v_mov_b32_e32 v9, v2
	v_mov_b32_e32 v10, v2
	v_mov_b32_e32 v11, v2
	v_mov_b32_e32 v12, v2
	v_mov_b32_e32 v13, v2
	v_mov_b32_e32 v14, v2
	v_mov_b32_e32 v15, v2
	v_mov_b32_e32 v16, v2
	v_mov_b32_e32 v17, v2
	v_mov_b32_e32 v18, v2
	v_mov_b32_e32 v19, v2
	v_mov_b32_e32 v20, v2
	v_mov_b32_e32 v21, v2
	v_mov_b32_e32 v22, v2
	v_mov_b32_e32 v23, v2
	v_mov_b32_e32 v24, v2
	v_mov_b32_e32 v25, v2
	v_mov_b32_e32 v26, v2
	v_mov_b32_e32 v27, v2
	v_mov_b32_e32 v28, v2
	v_mov_b32_e32 v29, v2
	v_mov_b32_e32 v30, v2
	v_mov_b32_e32 v31, v2
	v_mov_b32_e32 v32, v2
	v_mov_b32_e32 v33, v2
	v_mov_b32_e32 v34, v2
	v_mov_b32_e32 v35, v2
	v_mov_b32_e32 v36, v2
	v_mov_b32_e32 v37, v2
	v_mov_b32_e32 v38, v2
	v_mov_b32_e32 v39, v2
	v_mov_b32_e32 v40, v2
	v_mov_b32_e32 v41, v2
	v_mov_b32_e32 v42, v2
	v_mov_b32_e32 v43, v2
	v_mov_b32_e32 v44, v2
	v_mov_b32_e32 v45, v2
	v_mov_b32_e32 v46, v2
	v_mov_b32_e32 v47, v2
	v_mov_b32_e32 v48, v2
	v_mov_b32_e32 v49, v2
	v_mov_b32_e32 v50, v2
	v_mov_b32_e32 v51, v2
	v_mov_b32_e32 v52, v2
	v_mov_b32_e32 v53, v2
	v_mov_b32_e32 v54, v2
	v_mov_b32_e32 v55, v2
	v_mov_b32_e32 v56, v2
	v_mov_b32_e32 v57, v2
	v_mov_b32_e32 v58, v2
	v_mov_b32_e32 v59, v2
	v_mov_b32_e32 v60, v2
	v_mov_b32_e32 v61, v2
	v_mov_b32_e32 v62, v2
	v_mov_b32_e32 v63, v2
	v_mov_b32_e32 v64, v2
	v_mov_b32_e32 v65, v2
	v_mov_b32_e32 v66, v2
	v_mov_b32_e32 v67, v2
	v_mov_b32_e32 v68, v2
	v_mov_b32_e32 v69, v2
	v_mov_b32_e32 v70, v2
	v_mov_b32_e32 v71, v2
	v_mov_b32_e32 v72, v2
	v_mov_b32_e32 v73, v2
	v_mov_b32_e32 v74, v2
	v_mov_b32_e32 v75, v2
	v_mov_b32_e32 v76, v2
	v_mov_b32_e32 v77, v2
	v_mov_b32_e32 v78, v2
	v_mov_b32_e32 v79, v2
	s_waitcnt vmcnt(23)
	v_mov_b32_e32 v80, v2
	v_mov_b32_e32 v81, v2
	v_mov_b32_e32 v82, v2
	v_mov_b32_e32 v83, v2
	s_waitcnt vmcnt(22)
	v_mov_b32_e32 v84, v2
	v_mov_b32_e32 v85, v2
	v_mov_b32_e32 v86, v2
	v_mov_b32_e32 v87, v2
	s_waitcnt vmcnt(21)
	v_mov_b32_e32 v88, v2
	v_mov_b32_e32 v89, v2
	v_mov_b32_e32 v90, v2
	v_mov_b32_e32 v91, v2
	s_waitcnt vmcnt(20)
	v_mov_b32_e32 v92, v2
	v_mov_b32_e32 v93, v2
	v_mov_b32_e32 v94, v2
	v_mov_b32_e32 v95, v2
	v_mov_b32_e32 v96, v2
	v_mov_b32_e32 v97, v2
	v_mov_b32_e32 v98, v2
	v_mov_b32_e32 v99, v2
	v_mov_b32_e32 v100, v2
	v_mov_b32_e32 v101, v2
	v_mov_b32_e32 v102, v2
	v_mov_b32_e32 v103, v2
	v_mov_b32_e32 v104, v2
	v_mov_b32_e32 v105, v2
	v_mov_b32_e32 v106, v2
	v_mov_b32_e32 v107, v2
	v_mov_b32_e32 v108, v2
	v_mov_b32_e32 v109, v2
	v_mov_b32_e32 v110, v2
	v_mov_b32_e32 v111, v2
	v_mov_b32_e32 v112, v2
	v_mov_b32_e32 v113, v2
	v_mov_b32_e32 v114, v2
	v_mov_b32_e32 v115, v2
	v_mov_b32_e32 v116, v2
	v_mov_b32_e32 v117, v2
	v_mov_b32_e32 v118, v2
	v_mov_b32_e32 v119, v2
	v_mov_b32_e32 v120, v2
	v_mov_b32_e32 v121, v2
	v_mov_b32_e32 v122, v2
	v_mov_b32_e32 v123, v2
	v_mov_b32_e32 v124, v2
	v_mov_b32_e32 v125, v2
	v_mov_b32_e32 v126, v2
	v_mov_b32_e32 v127, v2
	v_mov_b32_e32 v128, v2
	v_mov_b32_e32 v129, v2
	s_branch .Lg3_loop
.Lg3_switch:
	s_mov_b64 s[4:5], s[12:13]
	s_mov_b64 s[6:7], s[10:11]
	s_add_u32 s56, s6, 0xfffff000
	s_addc_u32 s57, s7, -1
	s_mov_b32 s35, s38
	s_mov_b32 s74, -2
	s_branch .Lg3_noswitch
.Lg3_loop:
	s_waitcnt lgkmcnt(0)
	s_barrier
	ds_read_b128 v[228:231], v174
	ds_read_b128 v[232:235], v174 offset:2048
	ds_read_b128 v[236:239], v174 offset:4096
	ds_read_b128 v[240:243], v174 offset:6144
	ds_read_b128 v[248:251], v171
	ds_read_b128 v[252:255], v171 offset:4096
	s_lshl_b32 s0, s35, 1
	s_add_i32 s0, s0, s74
	s_and_b32 s40, s0, 30
	s_lshl_b32 s40, s40, 6
	s_add_u32 s40, s56, s40
	s_addc_u32 s41, s57, 0
	s_add_i32 s32, s75, s76
	s_mov_b32 m0, s32
	s_waitcnt lgkmcnt(5)
	v_mfma_f32_32x32x16_bf16 v[114:129], v[220:223], v[228:231], v[114:129]
	global_load_lds_dwordx4 v162, s[40:41]
	v_mfma_f32_32x32x16_bf16 v[50:65], v[224:227], v[228:231], v[50:65]
	ds_read_b128 v[228:231], v175
	s_waitcnt lgkmcnt(5)
	v_mfma_f32_32x32x16_bf16 v[98:113], v[220:223], v[232:235], v[98:113]
	global_load_lds_dwordx4 v163, s[40:41] offset:1024
	v_mfma_f32_32x32x16_bf16 v[34:49], v[224:227], v[232:235], v[34:49]
	ds_read_b128 v[232:235], v175 offset:2048
	s_waitcnt lgkmcnt(5)
	v_mfma_f32_32x32x16_bf16 v[82:97], v[220:223], v[236:239], v[82:97]
	global_load_lds_dwordx4 v164, s[40:41] offset:2048
	v_mfma_f32_32x32x16_bf16 v[18:33], v[224:227], v[236:239], v[18:33]
	ds_read_b128 v[236:239], v175 offset:4096
	s_waitcnt lgkmcnt(5)
	v_mfma_f32_32x32x16_bf16 v[66:81], v[220:223], v[240:243], v[66:81]
	global_load_lds_dwordx4 v165, s[40:41] offset:3072
	s_add_u32 m0, m0, 0x1000
	v_mfma_f32_32x32x16_bf16 v[2:17], v[224:227], v[240:243], v[2:17]
	ds_read_b128 v[240:243], v175 offset:6144
	ds_read_b128 v[220:223], v172
	ds_read_b128 v[224:227], v172 offset:4096
	s_waitcnt vmcnt(8)
	v_cvt_pk_bf16_f32 v190, v146, v150
	v_cvt_pk_bf16_f32 v191, v154, v158
	v_cvt_pk_bf16_f32 v192, v147, v151
	v_cvt_pk_bf16_f32 v193, v155, v159
	s_waitcnt lgkmcnt(5)
	v_mfma_f32_32x32x16_bf16 v[114:129], v[248:251], v[228:231], v[114:129]
	global_load_lds_dwordx4 v166, s[40:41]
	ds_write2st64_b64 v176, v[190:191], v[192:193] offset0:16 offset1:20
	v_cvt_pk_bf16_f32 v194, v148, v152
	v_cvt_pk_bf16_f32 v195, v156, v160
	v_cvt_pk_bf16_f32 v190, v149, v153
	v_cvt_pk_bf16_f32 v191, v157, v161
	v_mfma_f32_32x32x16_bf16 v[50:65], v[252:255], v[228:231], v[50:65]
	global_load_lds_dwordx4 v167, s[40:41] offset:1024
	ds_write2st64_b64 v176, v[194:195], v[190:191] offset0:24 offset1:28
	s_add_i32 s0, s0, 1
	s_and_b32 s58, s0, 31
	s_lshl_b32 s58, s58, 17
	s_add_u32 s58, s4, s58
	s_addc_u32 s59, s5, 0
	s_add_u32 s60, s58, 0x1000
	s_addc_u32 s61, s59, 0
	s_add_u32 s62, s58, s33
	s_addc_u32 s63, s59, 0
	s_add_u32 s64, s58, 0x3000
	s_addc_u32 s65, s59, 0
	s_waitcnt lgkmcnt(6)
	v_mfma_f32_32x32x16_bf16 v[98:113], v[248:251], v[232:235], v[98:113]
	global_load_lds_dwordx4 v168, s[40:41] offset:2048
	v_mfma_f32_32x32x16_bf16 v[34:49], v[252:255], v[232:235], v[34:49]
	global_load_lds_dwordx4 v169, s[40:41] offset:3072
	s_waitcnt lgkmcnt(5)
	v_mfma_f32_32x32x16_bf16 v[82:97], v[248:251], v[236:239], v[82:97]
	global_load_dwordx4 v[146:149], v177, s[58:59]
	v_mfma_f32_32x32x16_bf16 v[18:33], v[252:255], v[236:239], v[18:33]
	global_load_dwordx4 v[150:153], v177, s[60:61]
	s_waitcnt lgkmcnt(4)
	v_mfma_f32_32x32x16_bf16 v[66:81], v[248:251], v[240:243], v[66:81]
	global_load_dwordx4 v[154:157], v177, s[62:63]
	v_mfma_f32_32x32x16_bf16 v[2:17], v[252:255], v[240:243], v[2:17]
	global_load_dwordx4 v[158:161], v177, s[64:65]
	s_waitcnt lgkmcnt(0)
	s_barrier
	ds_read_b128 v[228:231], v174 offset:8192
	ds_read_b128 v[232:235], v174 offset:10240
	ds_read_b128 v[236:239], v174 offset:12288
	ds_read_b128 v[240:243], v174 offset:14336
	ds_read_b128 v[248:251], v173
	ds_read_b128 v[252:255], v173 offset:4096
	s_cmp_eq_u32 s39, 14
	s_cbranch_scc1 .Lg3_switch
.Lg3_noswitch:
	s_waitcnt lgkmcnt(5)
	v_mfma_f32_32x32x16_bf16 v[114:129], v[220:223], v[228:231], v[114:129]
	v_mfma_f32_32x32x16_bf16 v[50:65], v[224:227], v[228:231], v[50:65]
	ds_read_b128 v[228:231], v175 offset:8192
	s_waitcnt lgkmcnt(5)
	v_mfma_f32_32x32x16_bf16 v[98:113], v[220:223], v[232:235], v[98:113]
	v_mfma_f32_32x32x16_bf16 v[34:49], v[224:227], v[232:235], v[34:49]
	ds_read_b128 v[232:235], v175 offset:10240
	s_waitcnt lgkmcnt(5)
	v_mfma_f32_32x32x16_bf16 v[82:97], v[220:223], v[236:239], v[82:97]
	v_mfma_f32_32x32x16_bf16 v[18:33], v[224:227], v[236:239], v[18:33]
	ds_read_b128 v[236:239], v175 offset:12288
	s_waitcnt lgkmcnt(5)
	v_mfma_f32_32x32x16_bf16 v[66:81], v[220:223], v[240:243], v[66:81]
	v_mfma_f32_32x32x16_bf16 v[2:17], v[224:227], v[240:243], v[2:17]
	ds_read_b128 v[240:243], v175 offset:14336
	s_waitcnt vmcnt(12)
	v_cvt_pk_bf16_f32 v190, v130, v134
	v_cvt_pk_bf16_f32 v191, v138, v142
	v_cvt_pk_bf16_f32 v192, v131, v135
	v_cvt_pk_bf16_f32 v193, v139, v143
	s_waitcnt lgkmcnt(3)
	v_mfma_f32_32x32x16_bf16 v[114:129], v[248:251], v[228:231], v[114:129]
	ds_write2st64_b64 v176, v[190:191], v[192:193] offset0:0 offset1:4
	v_cvt_pk_bf16_f32 v194, v132, v136
	v_cvt_pk_bf16_f32 v195, v140, v144
	v_cvt_pk_bf16_f32 v190, v133, v137
	v_cvt_pk_bf16_f32 v191, v141, v145
	v_mfma_f32_32x32x16_bf16 v[50:65], v[252:255], v[228:231], v[50:65]
	ds_write2st64_b64 v176, v[194:195], v[190:191] offset0:8 offset1:12
	s_lshl_b32 s0, s35, 1
	s_add_i32 s0, s0, s74
	s_add_i32 s0, s0, 2
	s_and_b32 s58, s0, 31
	s_lshl_b32 s58, s58, 17
	s_add_u32 s58, s4, s58
	s_addc_u32 s59, s5, 0
	s_add_u32 s60, s58, 0x1000
	s_addc_u32 s61, s59, 0
	s_add_u32 s62, s58, s33
	s_addc_u32 s63, s59, 0
	s_add_u32 s64, s58, 0x3000
	s_addc_u32 s65, s59, 0
	s_waitcnt lgkmcnt(4)
	v_mfma_f32_32x32x16_bf16 v[98:113], v[248:251], v[232:235], v[98:113]
	v_mfma_f32_32x32x16_bf16 v[34:49], v[252:255], v[232:235], v[34:49]
	s_waitcnt lgkmcnt(3)
	v_mfma_f32_32x32x16_bf16 v[82:97], v[248:251], v[236:239], v[82:97]
	global_load_dwordx4 v[130:133], v177, s[58:59]
	v_mfma_f32_32x32x16_bf16 v[18:33], v[252:255], v[236:239], v[18:33]
	global_load_dwordx4 v[134:137], v177, s[60:61]
	s_waitcnt lgkmcnt(2)
	v_mfma_f32_32x32x16_bf16 v[66:81], v[248:251], v[240:243], v[66:81]
	global_load_dwordx4 v[138:141], v177, s[62:63]
	v_mfma_f32_32x32x16_bf16 v[2:17], v[252:255], v[240:243], v[2:17]
	global_load_dwordx4 v[142:145], v177, s[64:65]
	s_xor_b32 s76, s76, 0x2000
	v_xor_b32_e32 v170, 0x2000, v170
	v_xor_b32_e32 v171, 0x2000, v171
	v_xor_b32_e32 v172, 0x2000, v172
	v_xor_b32_e32 v173, 0x2000, v173
	s_waitcnt vmcnt(8)
	ds_read_b128 v[220:223], v170
	ds_read_b128 v[224:227], v170 offset:4096
	s_add_i32 s74, s74, 2
	s_add_i32 s39, s39, 1
	s_cmp_lt_u32 s39, 16
	s_cbranch_scc1 .Lg3_loop
	s_branch .LBB0_1104

.LBB0_1355:
	s_or_b64 exec, exec, s[4:5]
	s_movk_i32 s12, 0xc0
	v_readlane_b32 s0, v245, 13
	s_barrier
	s_cmp_ge_i32 s0, s12
	s_cbranch_scc1 .LBB0_1366
	v_mov_b32_e32 v20, v187
	v_readlane_b32 s4, v245, 5
	v_readlane_b32 s5, v245, 6
	s_lshl_b32 s0, s85, 27
	v_lshrrev_b32_e32 v2, 3, v20
	v_and_b32_e32 v2, 7, v2
	v_and_b32_e32 v3, 0xc0, v20
	v_or_b32_e32 v178, v2, v3
	v_mov_b32_e32 v179, v1
	v_lshl_add_u64 v[2:3], v[178:179], 2, s[4:5]
	global_load_dword v162, v[2:3], off
	global_load_dword v163, v[2:3], off offset:32
	global_load_dword v164, v[2:3], off offset:64
	global_load_dword v165, v[2:3], off offset:96
	global_load_dword v166, v[2:3], off offset:128
	global_load_dword v167, v[2:3], off offset:160
	global_load_dword v168, v[2:3], off offset:192
	global_load_dword v169, v[2:3], off offset:224
	v_readlane_b32 s48, v247, 45
	v_readlane_b32 s49, v247, 46
	s_add_u32 s13, s48, s0
	s_addc_u32 s34, s49, 0
	v_readlane_b32 s4, v245, 7
	v_readlane_b32 s5, v245, 8
	s_add_u32 s0, s13, s4
	s_addc_u32 s4, s34, s5
	v_readlane_b32 s5, v245, 9
	s_add_u32 s6, s0, s5
	s_addc_u32 s7, s4, 0
	v_lshlrev_b32_e32 v4, 6, v20
	v_lshlrev_b32_e32 v5, 2, v20
	v_ashrrev_i32_e32 v23, 5, v20
	v_and_b32_e32 v4, 0x400, v4
	v_and_b32_e32 v2, 60, v5
	v_lshlrev_b32_e32 v5, 13, v23
	v_or3_b32 v190, v4, v5, v2
	v_mov_b32_e32 v191, v1
	v_lshlrev_b32_e32 v192, 2, v190
	s_movk_i32 s14, 0x4000
	v_bfe_u32 v197, v20, 5, 1
	v_and_b32_e32 v218, 0xffffffc0, v20
	v_lshlrev_b32_e32 v198, 1, v2
	v_and_b32_e32 v3, 31, v20
	v_cmp_gt_u32_e64 s[4:5], 16, v3
	v_cndmask_b32_e64 v4, 2, 0, s[4:5]
	v_lshlrev_b32_e32 v200, 1, v4
	v_readlane_b32 s35, v245, 16
	v_readlane_b32 s37, v245, 13
	v_readfirstlane_b32 s53, v20
	s_and_b32 s53, s53, 0xc0
	s_lshl_b32 s53, s53, 8
	s_movk_i32 s54, 0x2000
	v_lshrrev_b32_e32 v4, 1, v3
	v_and_b32_e32 v4, 7, v4
	v_xor_b32_e32 v4, v4, v197
	v_lshlrev_b32_e32 v4, 4, v4
	v_lshl_or_b32 v4, v3, 7, v4
	v_or_b32_e32 v216, s53, v4
	v_xor_b32_e32 v0, 32, v216
	v_xor_b32_e32 v180, 64, v216
	v_xor_b32_e32 v194, 0x60, v216
	v_lshrrev_b32_e32 v4, 2, v3
	v_and_b32_e32 v4, 3, v4
	v_xor_b32_e32 v5, v4, v197
	v_lshlrev_b32_e32 v5, 4, v5
	v_lshl_or_b32 v5, v3, 6, v5
	v_add_u32_e32 v217, 0x10000, v5
	v_xor_b32_e32 v209, 32, v217
	v_lshrrev_b32_e32 v5, 1, v23
	v_xor_b32_e32 v5, v5, v4
	v_lshlrev_b32_e32 v5, 4, v5
	v_and_b32_e32 v6, 1, v23
	v_lshl_or_b32 v5, v6, 3, v5
	v_lshl_or_b32 v5, v3, 6, v5
	v_add_u32_e32 v219, 0x10000, v5
	v_and_b32_e32 v4, 7, v20
	v_bfe_u32 v5, v20, 4, 2
	v_xor_b32_e32 v4, v4, v5
	v_lshlrev_b32_e32 v196, 4, v4
	v_xor_b32_e32 v215, 64, v196
	s_add_u32 s56, s22, 0xfffff000
	s_addc_u32 s57, s23, -1
	s_waitcnt vmcnt(0)
	v_lshl_add_u32 v162, v162, 11, v196
	v_lshl_add_u32 v163, v163, 11, v215
	v_lshl_add_u32 v164, v164, 11, v196
	v_lshl_add_u32 v165, v165, 11, v215
	v_lshl_add_u32 v166, v166, 11, v196
	v_lshl_add_u32 v167, v167, 11, v215
	v_lshl_add_u32 v168, v168, 11, v196
	v_lshl_add_u32 v169, v169, 11, v215
	v_add_u32_e32 v162, 0x1000, v162
	v_add_u32_e32 v163, 0xc00, v163
	v_add_u32_e32 v164, 0x800, v164
	v_add_u32_e32 v165, 0x400, v165
	v_add_u32_e32 v166, 0x1000, v166
	v_add_u32_e32 v167, 0xc00, v167
	v_add_u32_e32 v168, 0x800, v168
	v_add_u32_e32 v169, 0x400, v169
	s_lshl_b32 s0, s35, 1
	s_and_b32 s40, s0, 30
	s_lshl_b32 s40, s40, 6
	s_add_u32 s40, s56, s40
	s_addc_u32 s41, s57, 0
	s_mov_b32 m0, s53
	s_nop 0
	global_load_lds_dwordx4 v162, s[40:41]
	global_load_lds_dwordx4 v163, s[40:41] offset:1024
	global_load_lds_dwordx4 v164, s[40:41] offset:2048
	global_load_lds_dwordx4 v165, s[40:41] offset:3072
	s_add_u32 m0, m0, 0x1000
	s_nop 0
	global_load_lds_dwordx4 v166, s[40:41]
	global_load_lds_dwordx4 v167, s[40:41] offset:1024
	global_load_lds_dwordx4 v168, s[40:41] offset:2048
	global_load_lds_dwordx4 v169, s[40:41] offset:3072
	s_and_b32 s58, s0, 31
	s_lshl_b32 s58, s58, 18
	s_add_u32 s58, s6, s58
	s_addc_u32 s59, s7, 0
	s_add_u32 s60, s58, s33
	s_addc_u32 s61, s59, 0
	s_add_u32 s62, s58, s14
	s_addc_u32 s63, s59, 0
	s_add_u32 s64, s58, s97
	s_addc_u32 s65, s59, 0
	global_load_dwordx4 v[130:133], v192, s[58:59]
	global_load_dwordx4 v[134:137], v192, s[60:61]
	global_load_dwordx4 v[138:141], v192, s[62:63]
	global_load_dwordx4 v[142:145], v192, s[64:65]
	s_add_i32 s0, s0, 1
	s_and_b32 s58, s0, 31
	s_lshl_b32 s58, s58, 18
	s_add_u32 s58, s6, s58
	s_addc_u32 s59, s7, 0
	s_add_u32 s60, s58, s33
	s_addc_u32 s61, s59, 0
	s_add_u32 s62, s58, s14
	s_addc_u32 s63, s59, 0
	s_add_u32 s64, s58, s97
	s_addc_u32 s65, s59, 0
	global_load_dwordx4 v[146:149], v192, s[58:59]
	global_load_dwordx4 v[150:153], v192, s[60:61]
	global_load_dwordx4 v[154:157], v192, s[62:63]
	global_load_dwordx4 v[158:161], v192, s[64:65]
	s_waitcnt vmcnt(4)
	v_cvt_pk_bf16_f32 v202, v130, v134
	v_cvt_pk_bf16_f32 v203, v138, v142
	v_cvt_pk_bf16_f32 v204, v131, v135
	v_cvt_pk_bf16_f32 v205, v139, v143
	ds_write2st64_b64 v219, v[202:203], v[204:205] offset0:0 offset1:4
	v_cvt_pk_bf16_f32 v206, v132, v136
	v_cvt_pk_bf16_f32 v207, v140, v144
	v_cvt_pk_bf16_f32 v202, v133, v137
	v_cvt_pk_bf16_f32 v203, v141, v145
	ds_write2st64_b64 v219, v[206:207], v[202:203] offset0:8 offset1:12
	s_add_i32 s0, s0, 1
	s_and_b32 s58, s0, 31
	s_lshl_b32 s58, s58, 18
	s_add_u32 s58, s6, s58
	s_addc_u32 s59, s7, 0
	s_add_u32 s60, s58, s33
	s_addc_u32 s61, s59, 0
	s_add_u32 s62, s58, s14
	s_addc_u32 s63, s59, 0
	s_add_u32 s64, s58, s97
	s_addc_u32 s65, s59, 0
	global_load_dwordx4 v[130:133], v192, s[58:59]
	global_load_dwordx4 v[134:137], v192, s[60:61]
	global_load_dwordx4 v[138:141], v192, s[62:63]
	global_load_dwordx4 v[142:145], v192, s[64:65]
	ds_read_b128 v[220:223], v216
	ds_read_b128 v[224:227], v216 offset:4096
	s_branch .LBB0_1358

.Lg6_switch:
	v_mov_b32_e32 v162, v170
	v_mov_b32_e32 v163, v171
	v_mov_b32_e32 v164, v172
	v_mov_b32_e32 v165, v173
	v_mov_b32_e32 v166, v174
	v_mov_b32_e32 v167, v175
	v_mov_b32_e32 v168, v176
	v_mov_b32_e32 v169, v177
	s_mov_b64 s[6:7], s[10:11]
	s_mov_b32 s35, s38
	s_mov_b32 s52, -2
	s_branch .Lg6_noswitch
.Lg6_loop:
	s_waitcnt lgkmcnt(0)
	s_barrier
	ds_read_b128 v[228:231], v217
	ds_read_b128 v[232:235], v217 offset:2048
	ds_read_b128 v[236:239], v217 offset:4096
	ds_read_b128 v[240:243], v217 offset:6144
	ds_read_b128 v[248:251], v0
	ds_read_b128 v[252:255], v0 offset:4096
	s_lshl_b32 s0, s35, 1
	s_add_i32 s0, s0, s52
	s_and_b32 s40, s0, 30
	s_lshl_b32 s40, s40, 6
	s_add_u32 s40, s56, s40
	s_addc_u32 s41, s57, 0
	s_add_i32 s32, s53, s54
	s_mov_b32 m0, s32
	s_waitcnt lgkmcnt(5)
	v_mfma_f32_32x32x16_bf16 v[114:129], v[220:223], v[228:231], v[114:129]
	global_load_lds_dwordx4 v162, s[40:41]
	v_mfma_f32_32x32x16_bf16 v[50:65], v[224:227], v[228:231], v[50:65]
	ds_read_b128 v[228:231], v209
	s_waitcnt lgkmcnt(5)
	v_mfma_f32_32x32x16_bf16 v[98:113], v[220:223], v[232:235], v[98:113]
	global_load_lds_dwordx4 v163, s[40:41] offset:1024
	v_mfma_f32_32x32x16_bf16 v[34:49], v[224:227], v[232:235], v[34:49]
	ds_read_b128 v[232:235], v209 offset:2048
	s_waitcnt lgkmcnt(5)
	v_mfma_f32_32x32x16_bf16 v[82:97], v[220:223], v[236:239], v[82:97]
	global_load_lds_dwordx4 v164, s[40:41] offset:2048
	v_mfma_f32_32x32x16_bf16 v[18:33], v[224:227], v[236:239], v[18:33]
	ds_read_b128 v[236:239], v209 offset:4096
	s_waitcnt lgkmcnt(5)
	v_mfma_f32_32x32x16_bf16 v[66:81], v[220:223], v[240:243], v[66:81]
	global_load_lds_dwordx4 v165, s[40:41] offset:3072
	s_add_u32 m0, m0, 0x1000
	v_mfma_f32_32x32x16_bf16 v[2:17], v[224:227], v[240:243], v[2:17]
	ds_read_b128 v[240:243], v209 offset:6144
	ds_read_b128 v[220:223], v180
	ds_read_b128 v[224:227], v180 offset:4096
	s_waitcnt vmcnt(8)
	v_cvt_pk_bf16_f32 v202, v146, v150
	v_cvt_pk_bf16_f32 v203, v154, v158
	v_cvt_pk_bf16_f32 v204, v147, v151
	v_cvt_pk_bf16_f32 v205, v155, v159
	s_waitcnt lgkmcnt(5)
	v_mfma_f32_32x32x16_bf16 v[114:129], v[248:251], v[228:231], v[114:129]
	global_load_lds_dwordx4 v166, s[40:41]
	ds_write2st64_b64 v219, v[202:203], v[204:205] offset0:16 offset1:20
	v_cvt_pk_bf16_f32 v206, v148, v152
	v_cvt_pk_bf16_f32 v207, v156, v160
	v_cvt_pk_bf16_f32 v202, v149, v153
	v_cvt_pk_bf16_f32 v203, v157, v161
	v_mfma_f32_32x32x16_bf16 v[50:65], v[252:255], v[228:231], v[50:65]
	global_load_lds_dwordx4 v167, s[40:41] offset:1024
	ds_write2st64_b64 v219, v[206:207], v[202:203] offset0:24 offset1:28
	s_add_i32 s0, s0, 1
	s_and_b32 s58, s0, 31
	s_lshl_b32 s58, s58, 18
	s_add_u32 s58, s6, s58
	s_addc_u32 s59, s7, 0
	s_add_u32 s60, s58, s33
	s_addc_u32 s61, s59, 0
	s_add_u32 s62, s58, s14
	s_addc_u32 s63, s59, 0
	s_add_u32 s64, s58, s97
	s_addc_u32 s65, s59, 0
	s_waitcnt lgkmcnt(6)
	v_mfma_f32_32x32x16_bf16 v[98:113], v[248:251], v[232:235], v[98:113]
	global_load_lds_dwordx4 v168, s[40:41] offset:2048
	v_mfma_f32_32x32x16_bf16 v[34:49], v[252:255], v[232:235], v[34:49]
	global_load_lds_dwordx4 v169, s[40:41] offset:3072
	s_waitcnt lgkmcnt(5)
	v_mfma_f32_32x32x16_bf16 v[82:97], v[248:251], v[236:239], v[82:97]
	global_load_dwordx4 v[146:149], v192, s[58:59]
	v_mfma_f32_32x32x16_bf16 v[18:33], v[252:255], v[236:239], v[18:33]
	global_load_dwordx4 v[150:153], v192, s[60:61]
	s_waitcnt lgkmcnt(4)
	v_mfma_f32_32x32x16_bf16 v[66:81], v[248:251], v[240:243], v[66:81]
	global_load_dwordx4 v[154:157], v192, s[62:63]
	v_mfma_f32_32x32x16_bf16 v[2:17], v[252:255], v[240:243], v[2:17]
	global_load_dwordx4 v[158:161], v192, s[64:65]
	s_waitcnt lgkmcnt(0)
	s_barrier
	ds_read_b128 v[228:231], v217 offset:8192
	ds_read_b128 v[232:235], v217 offset:10240
	ds_read_b128 v[236:239], v217 offset:12288
	ds_read_b128 v[240:243], v217 offset:14336
	ds_read_b128 v[248:251], v194
	ds_read_b128 v[252:255], v194 offset:4096
	s_cmp_eq_u32 s39, 14
	s_cbranch_scc1 .Lg6_switch
.Lg6_noswitch:
	s_waitcnt lgkmcnt(5)
	v_mfma_f32_32x32x16_bf16 v[114:129], v[220:223], v[228:231], v[114:129]
	v_mfma_f32_32x32x16_bf16 v[50:65], v[224:227], v[228:231], v[50:65]
	ds_read_b128 v[228:231], v209 offset:8192
	s_waitcnt lgkmcnt(5)
	v_mfma_f32_32x32x16_bf16 v[98:113], v[220:223], v[232:235], v[98:113]
	v_mfma_f32_32x32x16_bf16 v[34:49], v[224:227], v[232:235], v[34:49]
	ds_read_b128 v[232:235], v209 offset:10240
	s_waitcnt lgkmcnt(5)
	v_mfma_f32_32x32x16_bf16 v[82:97], v[220:223], v[236:239], v[82:97]
	v_mfma_f32_32x32x16_bf16 v[18:33], v[224:227], v[236:239], v[18:33]
	ds_read_b128 v[236:239], v209 offset:12288
	s_waitcnt lgkmcnt(5)
	v_mfma_f32_32x32x16_bf16 v[66:81], v[220:223], v[240:243], v[66:81]
	v_mfma_f32_32x32x16_bf16 v[2:17], v[224:227], v[240:243], v[2:17]
	ds_read_b128 v[240:243], v209 offset:14336
	s_waitcnt vmcnt(12)
	v_cvt_pk_bf16_f32 v202, v130, v134
	v_cvt_pk_bf16_f32 v203, v138, v142
	v_cvt_pk_bf16_f32 v204, v131, v135
	v_cvt_pk_bf16_f32 v205, v139, v143
	s_waitcnt lgkmcnt(3)
	v_mfma_f32_32x32x16_bf16 v[114:129], v[248:251], v[228:231], v[114:129]
	ds_write2st64_b64 v219, v[202:203], v[204:205] offset0:0 offset1:4
	v_cvt_pk_bf16_f32 v206, v132, v136
	v_cvt_pk_bf16_f32 v207, v140, v144
	v_cvt_pk_bf16_f32 v202, v133, v137
	v_cvt_pk_bf16_f32 v203, v141, v145
	v_mfma_f32_32x32x16_bf16 v[50:65], v[252:255], v[228:231], v[50:65]
	ds_write2st64_b64 v219, v[206:207], v[202:203] offset0:8 offset1:12
	s_lshl_b32 s0, s35, 1
	s_add_i32 s0, s0, s52
	s_add_i32 s0, s0, 2
	s_and_b32 s58, s0, 31
	s_lshl_b32 s58, s58, 18
	s_add_u32 s58, s6, s58
	s_addc_u32 s59, s7, 0
	s_add_u32 s60, s58, s33
	s_addc_u32 s61, s59, 0
	s_add_u32 s62, s58, s14
	s_addc_u32 s63, s59, 0
	s_add_u32 s64, s58, s97
	s_addc_u32 s65, s59, 0
	s_waitcnt lgkmcnt(4)
	v_mfma_f32_32x32x16_bf16 v[98:113], v[248:251], v[232:235], v[98:113]
	v_mfma_f32_32x32x16_bf16 v[34:49], v[252:255], v[232:235], v[34:49]
	s_waitcnt lgkmcnt(3)
	v_mfma_f32_32x32x16_bf16 v[82:97], v[248:251], v[236:239], v[82:97]
	global_load_dwordx4 v[130:133], v192, s[58:59]
	v_mfma_f32_32x32x16_bf16 v[18:33], v[252:255], v[236:239], v[18:33]
	global_load_dwordx4 v[134:137], v192, s[60:61]
	s_waitcnt lgkmcnt(2)
	v_mfma_f32_32x32x16_bf16 v[66:81], v[248:251], v[240:243], v[66:81]
	global_load_dwordx4 v[138:141], v192, s[62:63]
	v_mfma_f32_32x32x16_bf16 v[2:17], v[252:255], v[240:243], v[2:17]
	global_load_dwordx4 v[142:145], v192, s[64:65]
	s_xor_b32 s54, s54, 0x2000
	v_xor_b32_e32 v216, 0x2000, v216
	v_xor_b32_e32 v0, 0x2000, v0
	v_xor_b32_e32 v180, 0x2000, v180
	v_xor_b32_e32 v194, 0x2000, v194
	s_waitcnt vmcnt(8)
	ds_read_b128 v[220:223], v216
	ds_read_b128 v[224:227], v216 offset:4096
	s_add_i32 s52, s52, 2
	s_add_i32 s39, s39, 1
	s_cmp_lt_u32 s39, 16
	s_cbranch_scc1 .Lg6_loop
	s_branch .LBB0_1357

	.amdhsa_kernel _Z4mega6Params
		.amdhsa_group_segment_fixed_size 8192
		.amdhsa_private_segment_fixed_size 0
		.amdhsa_kernarg_size 616
		.amdhsa_user_sgpr_count 2
		.amdhsa_user_sgpr_dispatch_ptr 0
		.amdhsa_user_sgpr_queue_ptr 0
		.amdhsa_user_sgpr_kernarg_segment_ptr 1
		.amdhsa_user_sgpr_dispatch_id 0
		.amdhsa_user_sgpr_kernarg_preload_length 0
		.amdhsa_user_sgpr_kernarg_preload_offset 0
		.amdhsa_user_sgpr_private_segment_size 0
		.amdhsa_uses_dynamic_stack 0
		.amdhsa_enable_private_segment 0
		.amdhsa_system_sgpr_workgroup_id_x 1
		.amdhsa_system_sgpr_workgroup_id_y 0
		.amdhsa_system_sgpr_workgroup_id_z 0
		.amdhsa_system_sgpr_workgroup_info 0
		.amdhsa_system_vgpr_workitem_id 2
		.amdhsa_next_free_vgpr 256
		.amdhsa_next_free_sgpr 100
		.amdhsa_accum_offset 256
		.amdhsa_reserve_vcc 1
		.amdhsa_float_round_mode_32 0
		.amdhsa_float_round_mode_16_64 0
		.amdhsa_float_denorm_mode_32 3
		.amdhsa_float_denorm_mode_16_64 3
		.amdhsa_dx10_clamp 1
		.amdhsa_ieee_mode 1
		.amdhsa_fp16_overflow 0
		.amdhsa_tg_split 0
		.amdhsa_exception_fp_ieee_invalid_op 0
		.amdhsa_exception_fp_denorm_src 0
		.amdhsa_exception_fp_ieee_div_zero 0
		.amdhsa_exception_fp_ieee_overflow 0
		.amdhsa_exception_fp_ieee_underflow 0
		.amdhsa_exception_fp_ieee_inexact 0
		.amdhsa_exception_int_div_zero 0
	.end_amdhsa_kernel

amdhsa.kernels:
  - .agpr_count:     0
    .args:
      - .offset:         0
        .size:           360
        .value_kind:     by_value
      - .offset:         360
        .size:           4
        .value_kind:     hidden_block_count_x
      - .offset:         364
        .size:           4
        .value_kind:     hidden_block_count_y
      - .offset:         368
        .size:           4
        .value_kind:     hidden_block_count_z
      - .offset:         372
        .size:           2
        .value_kind:     hidden_group_size_x
      - .offset:         374
        .size:           2
        .value_kind:     hidden_group_size_y
      - .offset:         376
        .size:           2
        .value_kind:     hidden_group_size_z
      - .offset:         378
        .size:           2
        .value_kind:     hidden_remainder_x
      - .offset:         380
        .size:           2
        .value_kind:     hidden_remainder_y
      - .offset:         382
        .size:           2
        .value_kind:     hidden_remainder_z
      - .offset:         400
        .size:           8
        .value_kind:     hidden_global_offset_x
      - .offset:         408
        .size:           8
        .value_kind:     hidden_global_offset_y
      - .offset:         416
        .size:           8
        .value_kind:     hidden_global_offset_z
      - .offset:         424
        .size:           2
        .value_kind:     hidden_grid_dims
      - .offset:         448
        .size:           8
        .value_kind:     hidden_multigrid_sync_arg
      - .offset:         480
        .size:           4
        .value_kind:     hidden_dynamic_lds_size
    .group_segment_fixed_size: 8192
    .kernarg_segment_align: 8
    .kernarg_segment_size: 616
    .language:       OpenCL C
    .language_version:
      - 2
      - 0
    .max_flat_workgroup_size: 256
    .name:           _Z4mega6Params
    .private_segment_fixed_size: 0
    .sgpr_count:     106
    .sgpr_spill_count: 229
    .symbol:         _Z4mega6Params.kd
    .uniform_work_group_size: 1
    .uses_dynamic_stack: false
    .vgpr_count:     256
    .vgpr_spill_count: 0
    .wavefront_size: 64
